# phase 5 GEMM epilogue hand-written with four residual row-groups in flight
# baseline (speedup 1.0000x reference)
.LBB0_686:
	v_and_b32_e32 v114, 15, v77
	v_bfe_u32 v115, v77, 4, 2
	s_lshl_b32 s0, s26, 8
	s_lshl_b32 s1, s80, 6
	s_add_i32 s0, s0, s1
	v_add_u32_e32 v116, s0, v114
	s_lshl_b32 s1, s62, 8
	s_lshl_b32 s19, s53, 5
	s_add_i32 s1, s1, s19
	v_lshl_add_u32 v117, v115, 2, s1
	v_mov_b32_e32 v119, 0
	v_mov_b32_e32 v118, v116
	v_lshlrev_b32_e32 v120, 2, v117
	v_mov_b32_e32 v121, 0
	s_sub_i32 s19, s26, 32
	s_ashr_i32 s19, s19, 3
	s_add_i32 s19, s19, 1
	s_cmp_lt_i32 s26, 32
	s_cselect_b32 s19, 0, s19
	v_readlane_b32 s36, v126, 15
	v_readlane_b32 s37, v126, 16
	v_readlane_b32 s38, v126, 17
	v_readlane_b32 s39, v126, 18
	v_readlane_b32 s42, v126, 8
	v_readlane_b32 s43, v126, 9
	s_sub_u32 s38, s38, 0x2000000
	s_subb_u32 s39, s39, 0
	s_cmp_lt_i32 s26, 32
	s_cselect_b32 s28, s36, s38
	s_cselect_b32 s29, s37, s39
	v_lshlrev_b64 v[106:107], 12, v[118:119]
	v_lshl_add_u64 v[106:107], v[106:107], 0, s[28:29]
	v_lshl_add_u64 v[106:107], v[106:107], 0, v[120:121]
	s_mul_i32 s19, s19, 0x6000
	s_add_u32 s30, s42, 0x18e82000
	s_addc_u32 s31, s43, 0
	s_add_u32 s30, s30, s19
	s_addc_u32 s31, s31, 0
	v_lshl_add_u64 v[108:109], s[30:31], 0, v[120:121]
	v_lshlrev_b32_e32 v120, 1, v117
	v_lshlrev_b64 v[110:111], 11, v[118:119]
	v_lshl_add_u64 v[110:111], v[110:111], 0, s[10:11]
	v_lshl_add_u64 v[110:111], v[110:111], 0, v[120:121]
	global_load_dwordx4 v[84:87], v[108:109], off
	global_load_dwordx4 v[88:91], v[108:109], off offset:64
	global_load_dwordx4 v[92:95], v[108:109], off offset:512
	global_load_dwordx4 v[96:99], v[108:109], off offset:576
	global_load_dwordx4 v[0:3], v[106:107], off
	global_load_dwordx4 v[4:7], v[106:107], off offset:64
	global_load_dwordx4 v[8:11], v[106:107], off offset:512
	global_load_dwordx4 v[12:15], v[106:107], off offset:576
	s_mov_b32 s28, 0x10000
	s_mov_b32 s29, 0
	v_lshl_add_u64 v[112:113], v[106:107], 0, s[28:29]
	global_load_dwordx4 v[16:19], v[112:113], off
	global_load_dwordx4 v[20:23], v[112:113], off offset:64
	global_load_dwordx4 v[24:27], v[112:113], off offset:512
	global_load_dwordx4 v[28:31], v[112:113], off offset:576
	s_mov_b32 s28, 0x20000
	s_mov_b32 s29, 0
	v_lshl_add_u64 v[112:113], v[106:107], 0, s[28:29]
	global_load_dwordx4 v[32:35], v[112:113], off
	global_load_dwordx4 v[36:39], v[112:113], off offset:64
	global_load_dwordx4 v[40:43], v[112:113], off offset:512
	global_load_dwordx4 v[44:47], v[112:113], off offset:576
	s_mov_b32 s28, 0x30000
	s_mov_b32 s29, 0
	v_lshl_add_u64 v[112:113], v[106:107], 0, s[28:29]
	global_load_dwordx4 v[48:51], v[112:113], off
	global_load_dwordx4 v[52:55], v[112:113], off offset:64
	global_load_dwordx4 v[56:59], v[112:113], off offset:512
	global_load_dwordx4 v[60:63], v[112:113], off offset:576
	s_waitcnt vmcnt(12)
	v_accvgpr_read_b32 v100, a0
	v_accvgpr_read_b32 v101, a1
	v_accvgpr_read_b32 v102, a2
	v_accvgpr_read_b32 v103, a3
	v_pk_mul_f32 v[0:1], v[0:1], s[16:17] op_sel_hi:[1,0]
	v_pk_mul_f32 v[2:3], v[2:3], s[16:17] op_sel_hi:[1,0]
	v_pk_fma_f32 v[100:101], v[100:101], v[84:85], v[0:1]
	v_pk_fma_f32 v[102:103], v[102:103], v[86:87], v[2:3]
	v_cvt_pk_bf16_f32 v104, v100, v101
	v_cvt_pk_bf16_f32 v105, v102, v103
	global_store_dwordx2 v[110:111], v[104:105], off
	v_accvgpr_read_b32 v100, a4
	v_accvgpr_read_b32 v101, a5
	v_accvgpr_read_b32 v102, a6
	v_accvgpr_read_b32 v103, a7
	v_pk_mul_f32 v[4:5], v[4:5], s[16:17] op_sel_hi:[1,0]
	v_pk_mul_f32 v[6:7], v[6:7], s[16:17] op_sel_hi:[1,0]
	v_pk_fma_f32 v[100:101], v[100:101], v[88:89], v[4:5]
	v_pk_fma_f32 v[102:103], v[102:103], v[90:91], v[6:7]
	v_cvt_pk_bf16_f32 v104, v100, v101
	v_cvt_pk_bf16_f32 v105, v102, v103
	global_store_dwordx2 v[110:111], v[104:105], off offset:32
	v_accvgpr_read_b32 v100, a32
	v_accvgpr_read_b32 v101, a33
	v_accvgpr_read_b32 v102, a34
	v_accvgpr_read_b32 v103, a35
	v_pk_mul_f32 v[8:9], v[8:9], s[16:17] op_sel_hi:[1,0]
	v_pk_mul_f32 v[10:11], v[10:11], s[16:17] op_sel_hi:[1,0]
	v_pk_fma_f32 v[100:101], v[100:101], v[92:93], v[8:9]
	v_pk_fma_f32 v[102:103], v[102:103], v[94:95], v[10:11]
	v_cvt_pk_bf16_f32 v104, v100, v101
	v_cvt_pk_bf16_f32 v105, v102, v103
	global_store_dwordx2 v[110:111], v[104:105], off offset:256
	v_accvgpr_read_b32 v100, a36
	v_accvgpr_read_b32 v101, a37
	v_accvgpr_read_b32 v102, a38
	v_accvgpr_read_b32 v103, a39
	v_pk_mul_f32 v[12:13], v[12:13], s[16:17] op_sel_hi:[1,0]
	v_pk_mul_f32 v[14:15], v[14:15], s[16:17] op_sel_hi:[1,0]
	v_pk_fma_f32 v[100:101], v[100:101], v[96:97], v[12:13]
	v_pk_fma_f32 v[102:103], v[102:103], v[98:99], v[14:15]
	v_cvt_pk_bf16_f32 v104, v100, v101
	v_cvt_pk_bf16_f32 v105, v102, v103
	global_store_dwordx2 v[110:111], v[104:105], off offset:288
	s_mov_b32 s28, 0x80000
	s_mov_b32 s29, 0
	v_lshl_add_u64 v[112:113], v[106:107], 0, s[28:29]
	global_load_dwordx4 v[0:3], v[112:113], off
	global_load_dwordx4 v[4:7], v[112:113], off offset:64
	global_load_dwordx4 v[8:11], v[112:113], off offset:512
	global_load_dwordx4 v[12:15], v[112:113], off offset:576
	s_waitcnt vmcnt(16)
	s_mov_b32 s28, 0x8000
	s_mov_b32 s29, 0
	v_lshl_add_u64 v[122:123], v[110:111], 0, s[28:29]
	v_accvgpr_read_b32 v100, a8
	v_accvgpr_read_b32 v101, a9
	v_accvgpr_read_b32 v102, a10
	v_accvgpr_read_b32 v103, a11
	v_pk_mul_f32 v[16:17], v[16:17], s[16:17] op_sel_hi:[1,0]
	v_pk_mul_f32 v[18:19], v[18:19], s[16:17] op_sel_hi:[1,0]
	v_pk_fma_f32 v[100:101], v[100:101], v[84:85], v[16:17]
	v_pk_fma_f32 v[102:103], v[102:103], v[86:87], v[18:19]
	v_cvt_pk_bf16_f32 v104, v100, v101
	v_cvt_pk_bf16_f32 v105, v102, v103
	global_store_dwordx2 v[122:123], v[104:105], off
	v_accvgpr_read_b32 v100, a12
	v_accvgpr_read_b32 v101, a13
	v_accvgpr_read_b32 v102, a14
	v_accvgpr_read_b32 v103, a15
	v_pk_mul_f32 v[20:21], v[20:21], s[16:17] op_sel_hi:[1,0]
	v_pk_mul_f32 v[22:23], v[22:23], s[16:17] op_sel_hi:[1,0]
	v_pk_fma_f32 v[100:101], v[100:101], v[88:89], v[20:21]
	v_pk_fma_f32 v[102:103], v[102:103], v[90:91], v[22:23]
	v_cvt_pk_bf16_f32 v104, v100, v101
	v_cvt_pk_bf16_f32 v105, v102, v103
	global_store_dwordx2 v[122:123], v[104:105], off offset:32
	v_accvgpr_read_b32 v100, a40
	v_accvgpr_read_b32 v101, a41
	v_accvgpr_read_b32 v102, a42
	v_accvgpr_read_b32 v103, a43
	v_pk_mul_f32 v[24:25], v[24:25], s[16:17] op_sel_hi:[1,0]
	v_pk_mul_f32 v[26:27], v[26:27], s[16:17] op_sel_hi:[1,0]
	v_pk_fma_f32 v[100:101], v[100:101], v[92:93], v[24:25]
	v_pk_fma_f32 v[102:103], v[102:103], v[94:95], v[26:27]
	v_cvt_pk_bf16_f32 v104, v100, v101
	v_cvt_pk_bf16_f32 v105, v102, v103
	global_store_dwordx2 v[122:123], v[104:105], off offset:256
	v_accvgpr_read_b32 v100, a44
	v_accvgpr_read_b32 v101, a45
	v_accvgpr_read_b32 v102, a46
	v_accvgpr_read_b32 v103, a47
	v_pk_mul_f32 v[28:29], v[28:29], s[16:17] op_sel_hi:[1,0]
	v_pk_mul_f32 v[30:31], v[30:31], s[16:17] op_sel_hi:[1,0]
	v_pk_fma_f32 v[100:101], v[100:101], v[96:97], v[28:29]
	v_pk_fma_f32 v[102:103], v[102:103], v[98:99], v[30:31]
	v_cvt_pk_bf16_f32 v104, v100, v101
	v_cvt_pk_bf16_f32 v105, v102, v103
	global_store_dwordx2 v[122:123], v[104:105], off offset:288
	s_mov_b32 s28, 0x90000
	s_mov_b32 s29, 0
	v_lshl_add_u64 v[112:113], v[106:107], 0, s[28:29]
	global_load_dwordx4 v[16:19], v[112:113], off
	global_load_dwordx4 v[20:23], v[112:113], off offset:64
	global_load_dwordx4 v[24:27], v[112:113], off offset:512
	global_load_dwordx4 v[28:31], v[112:113], off offset:576
	s_waitcnt vmcnt(20)
	s_mov_b32 s28, 0x10000
	s_mov_b32 s29, 0
	v_lshl_add_u64 v[122:123], v[110:111], 0, s[28:29]
	v_accvgpr_read_b32 v100, a16
	v_accvgpr_read_b32 v101, a17
	v_accvgpr_read_b32 v102, a18
	v_accvgpr_read_b32 v103, a19
	v_pk_mul_f32 v[32:33], v[32:33], s[16:17] op_sel_hi:[1,0]
	v_pk_mul_f32 v[34:35], v[34:35], s[16:17] op_sel_hi:[1,0]
	v_pk_fma_f32 v[100:101], v[100:101], v[84:85], v[32:33]
	v_pk_fma_f32 v[102:103], v[102:103], v[86:87], v[34:35]
	v_cvt_pk_bf16_f32 v104, v100, v101
	v_cvt_pk_bf16_f32 v105, v102, v103
	global_store_dwordx2 v[122:123], v[104:105], off
	v_accvgpr_read_b32 v100, a20
	v_accvgpr_read_b32 v101, a21
	v_accvgpr_read_b32 v102, a22
	v_accvgpr_read_b32 v103, a23
	v_pk_mul_f32 v[36:37], v[36:37], s[16:17] op_sel_hi:[1,0]
	v_pk_mul_f32 v[38:39], v[38:39], s[16:17] op_sel_hi:[1,0]
	v_pk_fma_f32 v[100:101], v[100:101], v[88:89], v[36:37]
	v_pk_fma_f32 v[102:103], v[102:103], v[90:91], v[38:39]
	v_cvt_pk_bf16_f32 v104, v100, v101
	v_cvt_pk_bf16_f32 v105, v102, v103
	global_store_dwordx2 v[122:123], v[104:105], off offset:32
	v_accvgpr_read_b32 v100, a48
	v_accvgpr_read_b32 v101, a49
	v_accvgpr_read_b32 v102, a50
	v_accvgpr_read_b32 v103, a51
	v_pk_mul_f32 v[40:41], v[40:41], s[16:17] op_sel_hi:[1,0]
	v_pk_mul_f32 v[42:43], v[42:43], s[16:17] op_sel_hi:[1,0]
	v_pk_fma_f32 v[100:101], v[100:101], v[92:93], v[40:41]
	v_pk_fma_f32 v[102:103], v[102:103], v[94:95], v[42:43]
	v_cvt_pk_bf16_f32 v104, v100, v101
	v_cvt_pk_bf16_f32 v105, v102, v103
	global_store_dwordx2 v[122:123], v[104:105], off offset:256
	v_accvgpr_read_b32 v100, a52
	v_accvgpr_read_b32 v101, a53
	v_accvgpr_read_b32 v102, a54
	v_accvgpr_read_b32 v103, a55
	v_pk_mul_f32 v[44:45], v[44:45], s[16:17] op_sel_hi:[1,0]
	v_pk_mul_f32 v[46:47], v[46:47], s[16:17] op_sel_hi:[1,0]
	v_pk_fma_f32 v[100:101], v[100:101], v[96:97], v[44:45]
	v_pk_fma_f32 v[102:103], v[102:103], v[98:99], v[46:47]
	v_cvt_pk_bf16_f32 v104, v100, v101
	v_cvt_pk_bf16_f32 v105, v102, v103
	global_store_dwordx2 v[122:123], v[104:105], off offset:288
	s_mov_b32 s28, 0xa0000
	s_mov_b32 s29, 0
	v_lshl_add_u64 v[112:113], v[106:107], 0, s[28:29]
	global_load_dwordx4 v[32:35], v[112:113], off
	global_load_dwordx4 v[36:39], v[112:113], off offset:64
	global_load_dwordx4 v[40:43], v[112:113], off offset:512
	global_load_dwordx4 v[44:47], v[112:113], off offset:576
	s_waitcnt vmcnt(24)
	s_mov_b32 s28, 0x18000
	s_mov_b32 s29, 0
	v_lshl_add_u64 v[122:123], v[110:111], 0, s[28:29]
	v_accvgpr_read_b32 v100, a24
	v_accvgpr_read_b32 v101, a25
	v_accvgpr_read_b32 v102, a26
	v_accvgpr_read_b32 v103, a27
	v_pk_mul_f32 v[48:49], v[48:49], s[16:17] op_sel_hi:[1,0]
	v_pk_mul_f32 v[50:51], v[50:51], s[16:17] op_sel_hi:[1,0]
	v_pk_fma_f32 v[100:101], v[100:101], v[84:85], v[48:49]
	v_pk_fma_f32 v[102:103], v[102:103], v[86:87], v[50:51]
	v_cvt_pk_bf16_f32 v104, v100, v101
	v_cvt_pk_bf16_f32 v105, v102, v103
	global_store_dwordx2 v[122:123], v[104:105], off
	v_accvgpr_read_b32 v100, a28
	v_accvgpr_read_b32 v101, a29
	v_accvgpr_read_b32 v102, a30
	v_accvgpr_read_b32 v103, a31
	v_pk_mul_f32 v[52:53], v[52:53], s[16:17] op_sel_hi:[1,0]
	v_pk_mul_f32 v[54:55], v[54:55], s[16:17] op_sel_hi:[1,0]
	v_pk_fma_f32 v[100:101], v[100:101], v[88:89], v[52:53]
	v_pk_fma_f32 v[102:103], v[102:103], v[90:91], v[54:55]
	v_cvt_pk_bf16_f32 v104, v100, v101
	v_cvt_pk_bf16_f32 v105, v102, v103
	global_store_dwordx2 v[122:123], v[104:105], off offset:32
	v_accvgpr_read_b32 v100, a56
	v_accvgpr_read_b32 v101, a57
	v_accvgpr_read_b32 v102, a58
	v_accvgpr_read_b32 v103, a59
	v_pk_mul_f32 v[56:57], v[56:57], s[16:17] op_sel_hi:[1,0]
	v_pk_mul_f32 v[58:59], v[58:59], s[16:17] op_sel_hi:[1,0]
	v_pk_fma_f32 v[100:101], v[100:101], v[92:93], v[56:57]
	v_pk_fma_f32 v[102:103], v[102:103], v[94:95], v[58:59]
	v_cvt_pk_bf16_f32 v104, v100, v101
	v_cvt_pk_bf16_f32 v105, v102, v103
	global_store_dwordx2 v[122:123], v[104:105], off offset:256
	v_accvgpr_read_b32 v100, a60
	v_accvgpr_read_b32 v101, a61
	v_accvgpr_read_b32 v102, a62
	v_accvgpr_read_b32 v103, a63
	v_pk_mul_f32 v[60:61], v[60:61], s[16:17] op_sel_hi:[1,0]
	v_pk_mul_f32 v[62:63], v[62:63], s[16:17] op_sel_hi:[1,0]
	v_pk_fma_f32 v[100:101], v[100:101], v[96:97], v[60:61]
	v_pk_fma_f32 v[102:103], v[102:103], v[98:99], v[62:63]
	v_cvt_pk_bf16_f32 v104, v100, v101
	v_cvt_pk_bf16_f32 v105, v102, v103
	global_store_dwordx2 v[122:123], v[104:105], off offset:288
	s_mov_b32 s28, 0xb0000
	s_mov_b32 s29, 0
	v_lshl_add_u64 v[112:113], v[106:107], 0, s[28:29]
	global_load_dwordx4 v[48:51], v[112:113], off
	global_load_dwordx4 v[52:55], v[112:113], off offset:64
	global_load_dwordx4 v[56:59], v[112:113], off offset:512
	global_load_dwordx4 v[60:63], v[112:113], off offset:576
	s_waitcnt vmcnt(24)
	s_mov_b32 s28, 0x40000
	s_mov_b32 s29, 0
	v_lshl_add_u64 v[122:123], v[110:111], 0, s[28:29]
	v_accvgpr_read_b32 v100, a64
	v_accvgpr_read_b32 v101, a65
	v_accvgpr_read_b32 v102, a66
	v_accvgpr_read_b32 v103, a67
	v_pk_mul_f32 v[0:1], v[0:1], s[16:17] op_sel_hi:[1,0]
	v_pk_mul_f32 v[2:3], v[2:3], s[16:17] op_sel_hi:[1,0]
	v_pk_fma_f32 v[100:101], v[100:101], v[84:85], v[0:1]
	v_pk_fma_f32 v[102:103], v[102:103], v[86:87], v[2:3]
	v_cvt_pk_bf16_f32 v104, v100, v101
	v_cvt_pk_bf16_f32 v105, v102, v103
	global_store_dwordx2 v[122:123], v[104:105], off
	v_accvgpr_read_b32 v100, a68
	v_accvgpr_read_b32 v101, a69
	v_accvgpr_read_b32 v102, a70
	v_accvgpr_read_b32 v103, a71
	v_pk_mul_f32 v[4:5], v[4:5], s[16:17] op_sel_hi:[1,0]
	v_pk_mul_f32 v[6:7], v[6:7], s[16:17] op_sel_hi:[1,0]
	v_pk_fma_f32 v[100:101], v[100:101], v[88:89], v[4:5]
	v_pk_fma_f32 v[102:103], v[102:103], v[90:91], v[6:7]
	v_cvt_pk_bf16_f32 v104, v100, v101
	v_cvt_pk_bf16_f32 v105, v102, v103
	global_store_dwordx2 v[122:123], v[104:105], off offset:32
	v_accvgpr_read_b32 v100, a96
	v_accvgpr_read_b32 v101, a97
	v_accvgpr_read_b32 v102, a98
	v_accvgpr_read_b32 v103, a99
	v_pk_mul_f32 v[8:9], v[8:9], s[16:17] op_sel_hi:[1,0]
	v_pk_mul_f32 v[10:11], v[10:11], s[16:17] op_sel_hi:[1,0]
	v_pk_fma_f32 v[100:101], v[100:101], v[92:93], v[8:9]
	v_pk_fma_f32 v[102:103], v[102:103], v[94:95], v[10:11]
	v_cvt_pk_bf16_f32 v104, v100, v101
	v_cvt_pk_bf16_f32 v105, v102, v103
	global_store_dwordx2 v[122:123], v[104:105], off offset:256
	v_accvgpr_read_b32 v100, a100
	v_accvgpr_read_b32 v101, a101
	v_accvgpr_read_b32 v102, a102
	v_accvgpr_read_b32 v103, a103
	v_pk_mul_f32 v[12:13], v[12:13], s[16:17] op_sel_hi:[1,0]
	v_pk_mul_f32 v[14:15], v[14:15], s[16:17] op_sel_hi:[1,0]
	v_pk_fma_f32 v[100:101], v[100:101], v[96:97], v[12:13]
	v_pk_fma_f32 v[102:103], v[102:103], v[98:99], v[14:15]
	v_cvt_pk_bf16_f32 v104, v100, v101
	v_cvt_pk_bf16_f32 v105, v102, v103
	global_store_dwordx2 v[122:123], v[104:105], off offset:288
	s_waitcnt vmcnt(20)
	s_mov_b32 s28, 0x48000
	s_mov_b32 s29, 0
	v_lshl_add_u64 v[122:123], v[110:111], 0, s[28:29]
	v_accvgpr_read_b32 v100, a72
	v_accvgpr_read_b32 v101, a73
	v_accvgpr_read_b32 v102, a74
	v_accvgpr_read_b32 v103, a75
	v_pk_mul_f32 v[16:17], v[16:17], s[16:17] op_sel_hi:[1,0]
	v_pk_mul_f32 v[18:19], v[18:19], s[16:17] op_sel_hi:[1,0]
	v_pk_fma_f32 v[100:101], v[100:101], v[84:85], v[16:17]
	v_pk_fma_f32 v[102:103], v[102:103], v[86:87], v[18:19]
	v_cvt_pk_bf16_f32 v104, v100, v101
	v_cvt_pk_bf16_f32 v105, v102, v103
	global_store_dwordx2 v[122:123], v[104:105], off
	v_accvgpr_read_b32 v100, a76
	v_accvgpr_read_b32 v101, a77
	v_accvgpr_read_b32 v102, a78
	v_accvgpr_read_b32 v103, a79
	v_pk_mul_f32 v[20:21], v[20:21], s[16:17] op_sel_hi:[1,0]
	v_pk_mul_f32 v[22:23], v[22:23], s[16:17] op_sel_hi:[1,0]
	v_pk_fma_f32 v[100:101], v[100:101], v[88:89], v[20:21]
	v_pk_fma_f32 v[102:103], v[102:103], v[90:91], v[22:23]
	v_cvt_pk_bf16_f32 v104, v100, v101
	v_cvt_pk_bf16_f32 v105, v102, v103
	global_store_dwordx2 v[122:123], v[104:105], off offset:32
	v_accvgpr_read_b32 v100, a104
	v_accvgpr_read_b32 v101, a105
	v_accvgpr_read_b32 v102, a106
	v_accvgpr_read_b32 v103, a107
	v_pk_mul_f32 v[24:25], v[24:25], s[16:17] op_sel_hi:[1,0]
	v_pk_mul_f32 v[26:27], v[26:27], s[16:17] op_sel_hi:[1,0]
	v_pk_fma_f32 v[100:101], v[100:101], v[92:93], v[24:25]
	v_pk_fma_f32 v[102:103], v[102:103], v[94:95], v[26:27]
	v_cvt_pk_bf16_f32 v104, v100, v101
	v_cvt_pk_bf16_f32 v105, v102, v103
	global_store_dwordx2 v[122:123], v[104:105], off offset:256
	v_accvgpr_read_b32 v100, a108
	v_accvgpr_read_b32 v101, a109
	v_accvgpr_read_b32 v102, a110
	v_accvgpr_read_b32 v103, a111
	v_pk_mul_f32 v[28:29], v[28:29], s[16:17] op_sel_hi:[1,0]
	v_pk_mul_f32 v[30:31], v[30:31], s[16:17] op_sel_hi:[1,0]
	v_pk_fma_f32 v[100:101], v[100:101], v[96:97], v[28:29]
	v_pk_fma_f32 v[102:103], v[102:103], v[98:99], v[30:31]
	v_cvt_pk_bf16_f32 v104, v100, v101
	v_cvt_pk_bf16_f32 v105, v102, v103
	global_store_dwordx2 v[122:123], v[104:105], off offset:288
	s_waitcnt vmcnt(16)
	s_mov_b32 s28, 0x50000
	s_mov_b32 s29, 0
	v_lshl_add_u64 v[122:123], v[110:111], 0, s[28:29]
	v_accvgpr_read_b32 v100, a80
	v_accvgpr_read_b32 v101, a81
	v_accvgpr_read_b32 v102, a82
	v_accvgpr_read_b32 v103, a83
	v_pk_mul_f32 v[32:33], v[32:33], s[16:17] op_sel_hi:[1,0]
	v_pk_mul_f32 v[34:35], v[34:35], s[16:17] op_sel_hi:[1,0]
	v_pk_fma_f32 v[100:101], v[100:101], v[84:85], v[32:33]
	v_pk_fma_f32 v[102:103], v[102:103], v[86:87], v[34:35]
	v_cvt_pk_bf16_f32 v104, v100, v101
	v_cvt_pk_bf16_f32 v105, v102, v103
	global_store_dwordx2 v[122:123], v[104:105], off
	v_accvgpr_read_b32 v100, a84
	v_accvgpr_read_b32 v101, a85
	v_accvgpr_read_b32 v102, a86
	v_accvgpr_read_b32 v103, a87
	v_pk_mul_f32 v[36:37], v[36:37], s[16:17] op_sel_hi:[1,0]
	v_pk_mul_f32 v[38:39], v[38:39], s[16:17] op_sel_hi:[1,0]
	v_pk_fma_f32 v[100:101], v[100:101], v[88:89], v[36:37]
	v_pk_fma_f32 v[102:103], v[102:103], v[90:91], v[38:39]
	v_cvt_pk_bf16_f32 v104, v100, v101
	v_cvt_pk_bf16_f32 v105, v102, v103
	global_store_dwordx2 v[122:123], v[104:105], off offset:32
	v_accvgpr_read_b32 v100, a112
	v_accvgpr_read_b32 v101, a113
	v_accvgpr_read_b32 v102, a114
	v_accvgpr_read_b32 v103, a115
	v_pk_mul_f32 v[40:41], v[40:41], s[16:17] op_sel_hi:[1,0]
	v_pk_mul_f32 v[42:43], v[42:43], s[16:17] op_sel_hi:[1,0]
	v_pk_fma_f32 v[100:101], v[100:101], v[92:93], v[40:41]
	v_pk_fma_f32 v[102:103], v[102:103], v[94:95], v[42:43]
	v_cvt_pk_bf16_f32 v104, v100, v101
	v_cvt_pk_bf16_f32 v105, v102, v103
	global_store_dwordx2 v[122:123], v[104:105], off offset:256
	v_accvgpr_read_b32 v100, a116
	v_accvgpr_read_b32 v101, a117
	v_accvgpr_read_b32 v102, a118
	v_accvgpr_read_b32 v103, a119
	v_pk_mul_f32 v[44:45], v[44:45], s[16:17] op_sel_hi:[1,0]
	v_pk_mul_f32 v[46:47], v[46:47], s[16:17] op_sel_hi:[1,0]
	v_pk_fma_f32 v[100:101], v[100:101], v[96:97], v[44:45]
	v_pk_fma_f32 v[102:103], v[102:103], v[98:99], v[46:47]
	v_cvt_pk_bf16_f32 v104, v100, v101
	v_cvt_pk_bf16_f32 v105, v102, v103
	global_store_dwordx2 v[122:123], v[104:105], off offset:288
	s_waitcnt vmcnt(12)
	s_mov_b32 s28, 0x58000
	s_mov_b32 s29, 0
	v_lshl_add_u64 v[122:123], v[110:111], 0, s[28:29]
	v_accvgpr_read_b32 v100, a88
	v_accvgpr_read_b32 v101, a89
	v_accvgpr_read_b32 v102, a90
	v_accvgpr_read_b32 v103, a91
	v_pk_mul_f32 v[48:49], v[48:49], s[16:17] op_sel_hi:[1,0]
	v_pk_mul_f32 v[50:51], v[50:51], s[16:17] op_sel_hi:[1,0]
	v_pk_fma_f32 v[100:101], v[100:101], v[84:85], v[48:49]
	v_pk_fma_f32 v[102:103], v[102:103], v[86:87], v[50:51]
	v_cvt_pk_bf16_f32 v104, v100, v101
	v_cvt_pk_bf16_f32 v105, v102, v103
	global_store_dwordx2 v[122:123], v[104:105], off
	v_accvgpr_read_b32 v100, a92
	v_accvgpr_read_b32 v101, a93
	v_accvgpr_read_b32 v102, a94
	v_accvgpr_read_b32 v103, a95
	v_pk_mul_f32 v[52:53], v[52:53], s[16:17] op_sel_hi:[1,0]
	v_pk_mul_f32 v[54:55], v[54:55], s[16:17] op_sel_hi:[1,0]
	v_pk_fma_f32 v[100:101], v[100:101], v[88:89], v[52:53]
	v_pk_fma_f32 v[102:103], v[102:103], v[90:91], v[54:55]
	v_cvt_pk_bf16_f32 v104, v100, v101
	v_cvt_pk_bf16_f32 v105, v102, v103
	global_store_dwordx2 v[122:123], v[104:105], off offset:32
	v_accvgpr_read_b32 v100, a120
	v_accvgpr_read_b32 v101, a121
	v_accvgpr_read_b32 v102, a122
	v_accvgpr_read_b32 v103, a123
	v_pk_mul_f32 v[56:57], v[56:57], s[16:17] op_sel_hi:[1,0]
	v_pk_mul_f32 v[58:59], v[58:59], s[16:17] op_sel_hi:[1,0]
	v_pk_fma_f32 v[100:101], v[100:101], v[92:93], v[56:57]
	v_pk_fma_f32 v[102:103], v[102:103], v[94:95], v[58:59]
	v_cvt_pk_bf16_f32 v104, v100, v101
	v_cvt_pk_bf16_f32 v105, v102, v103
	global_store_dwordx2 v[122:123], v[104:105], off offset:256
	v_accvgpr_read_b32 v100, a124
	v_accvgpr_read_b32 v101, a125
	v_accvgpr_read_b32 v102, a126
	v_accvgpr_read_b32 v103, a127
	v_pk_mul_f32 v[60:61], v[60:61], s[16:17] op_sel_hi:[1,0]
	v_pk_mul_f32 v[62:63], v[62:63], s[16:17] op_sel_hi:[1,0]
	v_pk_fma_f32 v[100:101], v[100:101], v[96:97], v[60:61]
	v_pk_fma_f32 v[102:103], v[102:103], v[98:99], v[62:63]
	v_cvt_pk_bf16_f32 v104, v100, v101
	v_cvt_pk_bf16_f32 v105, v102, v103
	global_store_dwordx2 v[122:123], v[104:105], off offset:288
	v_readlane_b32 s36, v126, 2
	v_readlane_b32 s37, v126, 3
	v_readlane_b32 s38, v126, 4
	v_readlane_b32 s39, v126, 5
	v_readlane_b32 s40, v126, 6
	v_readlane_b32 s41, v126, 7
	v_readlane_b32 s42, v126, 8
	v_readlane_b32 s43, v126, 9
	v_readlane_b32 s44, v126, 23
	v_readlane_b32 s45, v126, 24
	v_readlane_b32 s46, v126, 25
	v_readlane_b32 s47, v126, 26
	v_readlane_b32 s48, v126, 27
	v_readlane_b32 s49, v126, 28
	v_readlane_b32 s50, v126, 29
	v_readlane_b32 s51, v126, 30
	s_andn2_b64 vcc, exec, s[4:5]
	s_mov_b64 s[0:1], -1
	s_cbranch_vccnz .LBB0_675
	s_andn2_b64 vcc, exec, s[8:9]
	s_cbranch_vccnz .LBB0_674
	s_barrier
	s_branch .LBB0_674
